# out-proj GEMM: trickle-prefetch residual tile during K-loop, one wave per iteration issues a 64-line dummy load after the phase-4 wait
# speedup vs baseline: 1.0121x; 1.0121x over previous
; #define PG8_STAGE(bufoff, gbase, voff) do { _Pragma("unroll") for (int _i = 0; _i < 2; ++_i) \
;         __builtin_amdgcn_global_load_lds((const unsigned*)((const char*)(gbase) + (voff)[_i]), (LAS unsigned*)(lds + (bufoff) + ldsw + _i * 8192), 16, 0, 0); } while (0)
; #define PG8_LDA(dst, b, h) do { _Pragma("unroll") for (int m = 0; m < 4; ++m) _Pragma("unroll") for (int k = 0; k < 2; ++k) dst[m][k] = *(const LAS bf16x8*)(lds + PG8_SA(b, h) + aoff + m * 2048 + k * 1024); } while (0)
; #define PG8_LDB(dst, b, h) do { _Pragma("unroll") for (int n = 0; n < 2; ++n) _Pragma("unroll") for (int k = 0; k < 2; ++k) dst[n][k] = *(const LAS bf16x8*)(lds + PG8_SB(b, h) + boff + n * 2048 + k * 1024); } while (0)
; #define PG8_MMA(ai, bj, At, Bt) do { __builtin_amdgcn_s_setprio(1); _Pragma("unroll") for (int m = 0; m < 4; ++m) _Pragma("unroll") for (int n = 0; n < 2; ++n) _Pragma("unroll") for (int k = 0; k < 2; ++k) \
;         acc[ai][bj][m][n] = __builtin_amdgcn_mfma_f32_16x16x32_bf16(Bt[n][k], At[m][k], acc[ai][bj][m][n], 0, 0, 0); __builtin_amdgcn_s_setprio(0); } while (0)
; #define PG8_WAIT_V(n) asm volatile("s_waitcnt vmcnt(" #n ")" ::: "memory")
; #define PG8_WAIT_L(n) asm volatile("s_waitcnt lgkmcnt(" #n ")" ::: "memory")
; #define PG8_BAR __builtin_amdgcn_s_barrier()
; #define PG8_SCHED __builtin_amdgcn_sched_barrier(0)
; template <class Epi>
; __device__ __forceinline__ void gemm_phase(LAS unsigned char* lds, const Gemm g, const StaticOrder& S, const Epi& E) {
;     ...
;             PG8_LDB(B0, 0, 0); PG8_SCHED; PG8_LDA(At, 0, 0); PG8_STAGE(PG8_SA(1, 1), a1 + hstepA, voffA);
;             PG8_WAIT_L(8); PG8_BAR; PG8_WAIT_L(0); PG8_MMA(0, 0, At, B0); PG8_BAR; PG8_SCHED;
;             PG8_LDB(B1, 0, 1); PG8_STAGE(PG8_SB(0, 0), b2, voffB);
;             PG8_BAR; PG8_WAIT_L(0); PG8_MMA(0, 1, At, B1); PG8_BAR;
;             PG8_LDA(At, 0, 1); PG8_STAGE(PG8_SA(0, 0), a2, voffA);
;             PG8_BAR; PG8_WAIT_L(0); PG8_MMA(1, 0, At, B0); PG8_BAR; PG8_SCHED;
;             PG8_STAGE(PG8_SB(0, 1), b2 + hstepB, voffB);
;             PG8_WAIT_V(6); PG8_BAR; PG8_MMA(1, 1, At, B1); PG8_BAR;
.LBB0_359:
	s_add_u32 s26, s22, 0x100
	s_addc_u32 s27, s23, 0
	s_add_i32 s65, 0, 0x10000
	v_add_u32_e32 v86, s65, v209
	ds_read_b128 v[70:73], v86
	ds_read_b128 v[74:77], v86 offset:1024
	ds_read_b128 v[82:85], v86 offset:2048
	ds_read_b128 v[86:89], v86 offset:3072
	s_cmp_eq_u32 s64, 60
	s_cselect_b32 s25, s17, s27
	s_cselect_b32 s24, s60, s26
	s_cselect_b32 s37, s15, s63
	s_cselect_b32 s36, s61, s62
	v_lshl_add_u64 v[194:195], s[22:23], 0, v[190:191]
	s_add_i32 m0, s53, 0xc000
	ds_read_b128 v[146:149], v211
	ds_read_b128 v[150:153], v211 offset:1024
	ds_read_b128 v[154:157], v211 offset:2048
	ds_read_b128 v[158:161], v211 offset:3072
	ds_read_b128 v[162:165], v211 offset:4096
	ds_read_b128 v[166:169], v211 offset:5120
	ds_read_b128 v[170:173], v211 offset:6144
	ds_read_b128 v[184:187], v211 offset:7168
	global_load_lds_dwordx4 v[194:195], off
	v_lshl_add_u64 v[194:195], s[22:23], 0, v[192:193]
	s_add_i32 m0, s53, 0xe000
	s_nop 0
	global_load_lds_dwordx4 v[194:195], off
	s_waitcnt lgkmcnt(8)
	s_barrier
	s_waitcnt lgkmcnt(0)
	s_setprio 1
	s_waitcnt lgkmcnt(0)
	v_mfma_f32_16x16x32_bf16 v[142:145], v[70:73], v[146:149], v[142:145]
	v_mfma_f32_16x16x32_bf16 v[138:141], v[82:85], v[146:149], v[138:141]
	v_mfma_f32_16x16x32_bf16 v[126:129], v[70:73], v[154:157], v[126:129]
	v_mfma_f32_16x16x32_bf16 v[122:125], v[82:85], v[154:157], v[122:125]
	v_mfma_f32_16x16x32_bf16 v[110:113], v[70:73], v[162:165], v[110:113]
	v_mfma_f32_16x16x32_bf16 v[106:109], v[82:85], v[162:165], v[106:109]
	v_mfma_f32_16x16x32_bf16 v[94:97], v[70:73], v[170:173], v[94:97]
	v_mfma_f32_16x16x32_bf16 v[90:93], v[82:85], v[170:173], v[90:93]
	v_mfma_f32_16x16x32_bf16 v[142:145], v[74:77], v[150:153], v[142:145]
	v_mfma_f32_16x16x32_bf16 v[138:141], v[86:89], v[150:153], v[138:141]
	v_mfma_f32_16x16x32_bf16 v[126:129], v[74:77], v[158:161], v[126:129]
	v_mfma_f32_16x16x32_bf16 v[122:125], v[86:89], v[158:161], v[122:125]
	v_mfma_f32_16x16x32_bf16 v[110:113], v[74:77], v[166:169], v[110:113]
	v_mfma_f32_16x16x32_bf16 v[106:109], v[86:89], v[166:169], v[106:109]
	v_mfma_f32_16x16x32_bf16 v[94:97], v[74:77], v[184:187], v[94:97]
	v_mfma_f32_16x16x32_bf16 v[90:93], v[86:89], v[184:187], v[90:93]
	s_setprio 0
	s_barrier
	s_add_i32 s66, 0, 0x14000
	v_add_u32_e32 v206, s66, v209
	s_add_i32 s22, s65, s52
	ds_read_b128 v[194:197], v206
	ds_read_b128 v[198:201], v206 offset:1024
	ds_read_b128 v[202:205], v206 offset:2048
	ds_read_b128 v[212:215], v206 offset:3072
	v_lshl_add_u64 v[206:207], s[36:37], 0, v[0:1]
	s_mov_b32 m0, s22
	v_lshl_add_u64 v[216:217], s[36:37], 0, v[174:175]
	global_load_lds_dwordx4 v[206:207], off
	s_add_i32 m0, s22, 0x2000
	s_nop 0
	global_load_lds_dwordx4 v[216:217], off
	s_barrier
	s_waitcnt lgkmcnt(0)
	s_setprio 1
	s_waitcnt lgkmcnt(0)
	v_mfma_f32_16x16x32_bf16 v[134:137], v[194:197], v[146:149], v[134:137]
	v_mfma_f32_16x16x32_bf16 v[130:133], v[202:205], v[146:149], v[130:133]
	v_mfma_f32_16x16x32_bf16 v[118:121], v[194:197], v[154:157], v[118:121]
	v_mfma_f32_16x16x32_bf16 v[114:117], v[202:205], v[154:157], v[114:117]
	v_mfma_f32_16x16x32_bf16 v[102:105], v[194:197], v[162:165], v[102:105]
	v_mfma_f32_16x16x32_bf16 v[98:101], v[202:205], v[162:165], v[98:101]
	v_mfma_f32_16x16x32_bf16 v[78:81], v[194:197], v[170:173], v[78:81]
	v_mfma_f32_16x16x32_bf16 v[66:69], v[202:205], v[170:173], v[66:69]
	v_mfma_f32_16x16x32_bf16 v[134:137], v[198:201], v[150:153], v[134:137]
	v_mfma_f32_16x16x32_bf16 v[130:133], v[212:215], v[150:153], v[130:133]
	v_mfma_f32_16x16x32_bf16 v[118:121], v[198:201], v[158:161], v[118:121]
	v_mfma_f32_16x16x32_bf16 v[114:117], v[212:215], v[158:161], v[114:117]
	v_mfma_f32_16x16x32_bf16 v[102:105], v[198:201], v[166:169], v[102:105]
	v_mfma_f32_16x16x32_bf16 v[98:101], v[212:215], v[166:169], v[98:101]
	v_mfma_f32_16x16x32_bf16 v[78:81], v[198:201], v[184:187], v[78:81]
	v_mfma_f32_16x16x32_bf16 v[66:69], v[212:215], v[184:187], v[66:69]
	s_setprio 0
	s_mov_b32 m0, s53
	v_lshl_add_u64 v[218:219], s[24:25], 0, v[188:189]
	s_barrier
	ds_read_b128 v[146:149], v211 offset:16384
	ds_read_b128 v[150:153], v211 offset:17408
	ds_read_b128 v[154:157], v211 offset:18432
	ds_read_b128 v[158:161], v211 offset:19456
	ds_read_b128 v[162:165], v211 offset:20480
	ds_read_b128 v[166:169], v211 offset:21504
	ds_read_b128 v[170:173], v211 offset:22528
	ds_read_b128 v[184:187], v211 offset:23552
	global_load_lds_dwordx4 v[218:219], off
	v_lshl_add_u64 v[220:221], s[24:25], 0, v[176:177]
	s_mov_b32 m0, s54
	s_nop 0
	global_load_lds_dwordx4 v[220:221], off
	s_barrier
	s_waitcnt lgkmcnt(0)
	s_setprio 1
	s_waitcnt lgkmcnt(0)
	v_mfma_f32_16x16x32_bf16 v[62:65], v[70:73], v[146:149], v[62:65]
	v_mfma_f32_16x16x32_bf16 v[58:61], v[82:85], v[146:149], v[58:61]
	v_mfma_f32_16x16x32_bf16 v[46:49], v[70:73], v[154:157], v[46:49]
	v_mfma_f32_16x16x32_bf16 v[42:45], v[82:85], v[154:157], v[42:45]
	v_mfma_f32_16x16x32_bf16 v[30:33], v[70:73], v[162:165], v[30:33]
	v_mfma_f32_16x16x32_bf16 v[26:29], v[82:85], v[162:165], v[26:29]
	v_mfma_f32_16x16x32_bf16 v[14:17], v[70:73], v[170:173], v[14:17]
	v_mfma_f32_16x16x32_bf16 v[10:13], v[82:85], v[170:173], v[10:13]
	v_mfma_f32_16x16x32_bf16 v[62:65], v[74:77], v[150:153], v[62:65]
	v_mfma_f32_16x16x32_bf16 v[58:61], v[86:89], v[150:153], v[58:61]
	v_mfma_f32_16x16x32_bf16 v[46:49], v[74:77], v[158:161], v[46:49]
	v_mfma_f32_16x16x32_bf16 v[42:45], v[86:89], v[158:161], v[42:45]
	v_mfma_f32_16x16x32_bf16 v[30:33], v[74:77], v[166:169], v[30:33]
	v_mfma_f32_16x16x32_bf16 v[26:29], v[86:89], v[166:169], v[26:29]
	v_mfma_f32_16x16x32_bf16 v[14:17], v[74:77], v[184:187], v[14:17]
	v_mfma_f32_16x16x32_bf16 v[10:13], v[86:89], v[184:187], v[10:13]
	s_setprio 0
	s_barrier
	s_add_u32 s22, s36, 0x100000
	s_addc_u32 s23, s37, 0
	s_add_i32 s65, s66, s52
	v_lshl_add_u64 v[70:71], s[22:23], 0, v[0:1]
	s_mov_b32 m0, s65
	s_nop 0
	global_load_lds_dwordx4 v[70:71], off
	v_lshl_add_u64 v[70:71], s[22:23], 0, v[174:175]
	s_add_i32 m0, s65, 0x2000
	s_nop 0
	global_load_lds_dwordx4 v[70:71], off
	s_waitcnt vmcnt(6)
	s_barrier
	s_lshl_b32 vcc_lo, s64, 5
	s_and_b32 vcc_lo, vcc_lo, 0x1c0
	s_cmp_lg_u32 vcc_lo, s35
	s_cbranch_scc1 .Lwarm_skip_o
	global_load_dword v224, v222, s[100:101]
	s_add_u32 s100, s100, 0x80000
	s_addc_u32 s101, s101, 0
; #define PG8_STAGE(bufoff, gbase, voff) do { _Pragma("unroll") for (int _i = 0; _i < 2; ++_i) \
;         __builtin_amdgcn_global_load_lds((const unsigned*)((const char*)(gbase) + (voff)[_i]), (LAS unsigned*)(lds + (bufoff) + ldsw + _i * 8192), 16, 0, 0); } while (0)
; #define PG8_LDA(dst, b, h) do { _Pragma("unroll") for (int m = 0; m < 4; ++m) _Pragma("unroll") for (int k = 0; k < 2; ++k) dst[m][k] = *(const LAS bf16x8*)(lds + PG8_SA(b, h) + aoff + m * 2048 + k * 1024); } while (0)
; #define PG8_LDB(dst, b, h) do { _Pragma("unroll") for (int n = 0; n < 2; ++n) _Pragma("unroll") for (int k = 0; k < 2; ++k) dst[n][k] = *(const LAS bf16x8*)(lds + PG8_SB(b, h) + boff + n * 2048 + k * 1024); } while (0)
; #define PG8_MMA(ai, bj, At, Bt) do { __builtin_amdgcn_s_setprio(1); _Pragma("unroll") for (int m = 0; m < 4; ++m) _Pragma("unroll") for (int n = 0; n < 2; ++n) _Pragma("unroll") for (int k = 0; k < 2; ++k) \
;         acc[ai][bj][m][n] = __builtin_amdgcn_mfma_f32_16x16x32_bf16(Bt[n][k], At[m][k], acc[ai][bj][m][n], 0, 0, 0); __builtin_amdgcn_s_setprio(0); } while (0)
; #define PG8_WAIT_V(n) asm volatile("s_waitcnt vmcnt(" #n ")" ::: "memory")
; #define PG8_WAIT_L(n) asm volatile("s_waitcnt lgkmcnt(" #n ")" ::: "memory")
; #define PG8_BAR __builtin_amdgcn_s_barrier()
; #define PG8_SCHED __builtin_amdgcn_sched_barrier(0)
; template <class Epi>
; __device__ __forceinline__ void gemm_phase(LAS unsigned char* lds, const Gemm g, const StaticOrder& S, const Epi& E) {
;     ...
;             PG8_WAIT_V(6); PG8_BAR; PG8_MMA(1, 1, At, B1); PG8_BAR;
;             PG8_LDB(B0, 1, 0); PG8_SCHED; PG8_LDA(At, 1, 0); PG8_STAGE(PG8_SA(0, 1), a2 + hstepA, voffA);
;             PG8_WAIT_L(8); PG8_BAR; PG8_WAIT_L(0); PG8_MMA(0, 0, At, B0); PG8_BAR; PG8_SCHED;
;             PG8_LDB(B1, 1, 1); PG8_STAGE(PG8_SB(1, 0), b3, voffB);
;             PG8_BAR; PG8_WAIT_L(0); PG8_MMA(0, 1, At, B1); PG8_BAR;
.Lwarm_skip_o:
	s_setprio 1
	v_mfma_f32_16x16x32_bf16 v[54:57], v[194:197], v[146:149], v[54:57]
	v_mfma_f32_16x16x32_bf16 v[50:53], v[202:205], v[146:149], v[50:53]
	v_mfma_f32_16x16x32_bf16 v[38:41], v[194:197], v[154:157], v[38:41]
	v_mfma_f32_16x16x32_bf16 v[34:37], v[202:205], v[154:157], v[34:37]
	v_mfma_f32_16x16x32_bf16 v[22:25], v[194:197], v[162:165], v[22:25]
	v_mfma_f32_16x16x32_bf16 v[18:21], v[202:205], v[162:165], v[18:21]
	v_mfma_f32_16x16x32_bf16 v[6:9], v[194:197], v[170:173], v[6:9]
	v_mfma_f32_16x16x32_bf16 v[2:5], v[202:205], v[170:173], v[2:5]
	v_mfma_f32_16x16x32_bf16 v[54:57], v[198:201], v[150:153], v[54:57]
	v_mfma_f32_16x16x32_bf16 v[50:53], v[212:215], v[150:153], v[50:53]
	v_mfma_f32_16x16x32_bf16 v[38:41], v[198:201], v[158:161], v[38:41]
	v_mfma_f32_16x16x32_bf16 v[34:37], v[212:215], v[158:161], v[34:37]
	v_mfma_f32_16x16x32_bf16 v[22:25], v[198:201], v[166:169], v[22:25]
	v_mfma_f32_16x16x32_bf16 v[18:21], v[212:215], v[166:169], v[18:21]
	v_mfma_f32_16x16x32_bf16 v[6:9], v[198:201], v[184:187], v[6:9]
	v_mfma_f32_16x16x32_bf16 v[2:5], v[212:215], v[184:187], v[2:5]
	s_setprio 0
	s_add_i32 s65, 0, 0x18000
	v_add_u32_e32 v86, s65, v209
	s_barrier
	ds_read_b128 v[70:73], v86
	ds_read_b128 v[74:77], v86 offset:1024
	ds_read_b128 v[82:85], v86 offset:2048
	ds_read_b128 v[86:89], v86 offset:3072
	s_add_u32 s22, s24, 0x100000
	s_addc_u32 s23, s25, 0
	s_mov_b32 m0, s55
	v_lshl_add_u64 v[194:195], s[22:23], 0, v[188:189]
	ds_read_b128 v[146:149], v211 offset:32768
	ds_read_b128 v[150:153], v211 offset:33792
	ds_read_b128 v[154:157], v211 offset:34816
	ds_read_b128 v[158:161], v211 offset:35840
	ds_read_b128 v[162:165], v211 offset:36864
	ds_read_b128 v[166:169], v211 offset:37888
	ds_read_b128 v[170:173], v211 offset:38912
	ds_read_b128 v[184:187], v211 offset:39936
	global_load_lds_dwordx4 v[194:195], off
	v_lshl_add_u64 v[194:195], s[22:23], 0, v[176:177]
	s_mov_b32 m0, s56
	s_nop 0
	global_load_lds_dwordx4 v[194:195], off
	s_waitcnt lgkmcnt(8)
	s_barrier
	s_waitcnt lgkmcnt(0)
	s_setprio 1
	s_waitcnt lgkmcnt(0)
	v_mfma_f32_16x16x32_bf16 v[142:145], v[70:73], v[146:149], v[142:145]
	v_mfma_f32_16x16x32_bf16 v[138:141], v[82:85], v[146:149], v[138:141]
	v_mfma_f32_16x16x32_bf16 v[126:129], v[70:73], v[154:157], v[126:129]
	v_mfma_f32_16x16x32_bf16 v[122:125], v[82:85], v[154:157], v[122:125]
	v_mfma_f32_16x16x32_bf16 v[110:113], v[70:73], v[162:165], v[110:113]
	v_mfma_f32_16x16x32_bf16 v[106:109], v[82:85], v[162:165], v[106:109]
	v_mfma_f32_16x16x32_bf16 v[94:97], v[70:73], v[170:173], v[94:97]
	v_mfma_f32_16x16x32_bf16 v[90:93], v[82:85], v[170:173], v[90:93]
	v_mfma_f32_16x16x32_bf16 v[142:145], v[74:77], v[150:153], v[142:145]
	v_mfma_f32_16x16x32_bf16 v[138:141], v[86:89], v[150:153], v[138:141]
	v_mfma_f32_16x16x32_bf16 v[126:129], v[74:77], v[158:161], v[126:129]
	v_mfma_f32_16x16x32_bf16 v[122:125], v[86:89], v[158:161], v[122:125]
	v_mfma_f32_16x16x32_bf16 v[110:113], v[74:77], v[166:169], v[110:113]
	v_mfma_f32_16x16x32_bf16 v[106:109], v[86:89], v[166:169], v[106:109]
	v_mfma_f32_16x16x32_bf16 v[94:97], v[74:77], v[184:187], v[94:97]
	v_mfma_f32_16x16x32_bf16 v[90:93], v[86:89], v[184:187], v[90:93]
	s_setprio 0
	s_barrier
	s_add_i32 s24, 0, 0x1c000
	s_add_i32 s22, s65, s52
	v_add_u32_e32 v212, s24, v209
	v_lshl_add_u64 v[206:207], v[206:207], 0, s[6:7]
	s_mov_b32 m0, s22
	ds_read_b128 v[194:197], v212
	ds_read_b128 v[198:201], v212 offset:1024
	ds_read_b128 v[202:205], v212 offset:2048
	ds_read_b128 v[212:215], v212 offset:3072
	global_load_lds_dwordx4 v[206:207], off
	v_lshl_add_u64 v[206:207], v[216:217], 0, s[6:7]
	s_add_i32 m0, s22, 0x2000
	s_nop 0
	global_load_lds_dwordx4 v[206:207], off
	s_barrier
	s_waitcnt lgkmcnt(0)
	s_setprio 1
	s_waitcnt lgkmcnt(0)
	v_mfma_f32_16x16x32_bf16 v[134:137], v[194:197], v[146:149], v[134:137]
	v_mfma_f32_16x16x32_bf16 v[130:133], v[202:205], v[146:149], v[130:133]
	v_mfma_f32_16x16x32_bf16 v[118:121], v[194:197], v[154:157], v[118:121]
	v_mfma_f32_16x16x32_bf16 v[114:117], v[202:205], v[154:157], v[114:117]
	v_mfma_f32_16x16x32_bf16 v[102:105], v[194:197], v[162:165], v[102:105]
	v_mfma_f32_16x16x32_bf16 v[98:101], v[202:205], v[162:165], v[98:101]
	v_mfma_f32_16x16x32_bf16 v[78:81], v[194:197], v[170:173], v[78:81]
	v_mfma_f32_16x16x32_bf16 v[66:69], v[202:205], v[170:173], v[66:69]
	v_mfma_f32_16x16x32_bf16 v[134:137], v[198:201], v[150:153], v[134:137]
	v_mfma_f32_16x16x32_bf16 v[130:133], v[212:215], v[150:153], v[130:133]
	v_mfma_f32_16x16x32_bf16 v[118:121], v[198:201], v[158:161], v[118:121]
	v_mfma_f32_16x16x32_bf16 v[114:117], v[212:215], v[158:161], v[114:117]
	v_mfma_f32_16x16x32_bf16 v[102:105], v[198:201], v[166:169], v[102:105]
	v_mfma_f32_16x16x32_bf16 v[98:101], v[212:215], v[166:169], v[98:101]
	v_mfma_f32_16x16x32_bf16 v[78:81], v[198:201], v[184:187], v[78:81]
	v_mfma_f32_16x16x32_bf16 v[66:69], v[212:215], v[184:187], v[66:69]
	s_setprio 0
	s_mov_b32 m0, s58
	v_lshl_add_u64 v[206:207], v[218:219], 0, s[6:7]
	s_barrier
; __device__ __forceinline__ unsigned cvt_pk_bf16(float lo, float hi) { unsigned r; asm volatile("v_cvt_pk_bf16_f32 %0, %1, %2" : "=v"(r) : "v"(lo), "v"(hi)); return r; }
; #define PG8_BAR __builtin_amdgcn_s_barrier()
; template <class Epi>
; __device__ __forceinline__ void gemm_phase(LAS unsigned char* lds, const Gemm g, const StaticOrder& S, const Epi& E) {
;     ...
;             PG8_LDA(At, 1, 1); PG8_STAGE(PG8_SA(1, 0), a3, voffA);
;             PG8_BAR; PG8_WAIT_L(0); PG8_MMA(1, 0, At, B0); PG8_BAR; PG8_SCHED;
;             PG8_STAGE(PG8_SB(1, 1), b3 + hstepB, voffB);
;             PG8_WAIT_V(6); PG8_BAR; PG8_MMA(1, 1, At, B1); PG8_BAR;
;     __device__ __forceinline__ void operator()(const f32x4 (&acc)[2][2][4][2], const Unit& u, int wr, int wc, int fr, int fq, const Pre&) const {
;         const int row0 = u.pm * BM + wr * 64 + fr, col0 = u.pn * BM + wc * 32 + 4 * fq;
;         f32x4 gv[2][2];
; #pragma unroll
;         for (int bj = 0; bj < 2; ++bj)
; #pragma unroll
;             for (int n = 0; n < 2; ++n) gv[bj][n] = *(const f32x4*)(gnext + col0 + bj * HALF + n * 16);
;         f32x4 xb[2][2][2];
; #pragma unroll
;         for (int bj = 0; bj < 2; ++bj)
; #pragma unroll
;             for (int n = 0; n < 2; ++n) xb[0][bj][n] = *(const f32x4*)(Xin + (size_t)row0 * DM + col0 + bj * HALF + n * 16);
; #pragma unroll
;         for (int grp = 0; grp < 8; ++grp) { const int ai = grp >> 2, m = grp & 3, cur = grp & 1; const int r = row0 + ai * HALF + m * 16; float ss = 0.f;
;             if (grp < 7) { const int rn = row0 + ((grp + 1) >> 2) * HALF + ((grp + 1) & 3) * 16;
; #pragma unroll
;                 for (int bj = 0; bj < 2; ++bj)
; #pragma unroll
;                     for (int n = 0; n < 2; ++n) xb[cur ^ 1][bj][n] = *(const f32x4*)(Xin + (size_t)rn * DM + col0 + bj * HALF + n * 16); }
; #pragma unroll
;             for (int bj = 0; bj < 2; ++bj)
; #pragma unroll
;                 for (int n = 0; n < 2; ++n) { const int c = col0 + bj * HALF + n * 16;
;                     const f32x4 xv = xb[cur][bj][n] + acc[ai][bj][m][n]; *(f32x4*)(X + (size_t)r * DM + c) = xv;
;                     ss += (xv[0] * xv[0] + xv[1] * xv[1]) + (xv[2] * xv[2] + xv[3] * xv[3]);
;                     if (H) { const f32x4 hv = xv * gv[bj][n]; u32x2 w; w.x = cvt_pk_bf16(hv[0], hv[1]); w.y = cvt_pk_bf16(hv[2], hv[3]);
;                         *(u32x2*)(H + (size_t)r * DM + c) = w; } }
	ds_read_b128 v[146:149], v211 offset:49152
	ds_read_b128 v[150:153], v211 offset:50176
	ds_read_b128 v[154:157], v211 offset:51200
	ds_read_b128 v[158:161], v211 offset:52224
	ds_read_b128 v[162:165], v211 offset:53248
	ds_read_b128 v[166:169], v211 offset:54272
	ds_read_b128 v[170:173], v211 offset:55296
	ds_read_b128 v[184:187], v211 offset:56320
	global_load_lds_dwordx4 v[206:207], off
	v_lshl_add_u64 v[206:207], v[220:221], 0, s[6:7]
	s_mov_b32 m0, s59
	s_nop 0
	global_load_lds_dwordx4 v[206:207], off
	s_barrier
	s_waitcnt lgkmcnt(0)
	s_setprio 1
	s_waitcnt lgkmcnt(0)
	v_mfma_f32_16x16x32_bf16 v[62:65], v[70:73], v[146:149], v[62:65]
	v_mfma_f32_16x16x32_bf16 v[58:61], v[82:85], v[146:149], v[58:61]
	v_mfma_f32_16x16x32_bf16 v[46:49], v[70:73], v[154:157], v[46:49]
	v_mfma_f32_16x16x32_bf16 v[42:45], v[82:85], v[154:157], v[42:45]
	v_mfma_f32_16x16x32_bf16 v[30:33], v[70:73], v[162:165], v[30:33]
	v_mfma_f32_16x16x32_bf16 v[26:29], v[82:85], v[162:165], v[26:29]
	v_mfma_f32_16x16x32_bf16 v[14:17], v[70:73], v[170:173], v[14:17]
	v_mfma_f32_16x16x32_bf16 v[10:13], v[82:85], v[170:173], v[10:13]
	v_mfma_f32_16x16x32_bf16 v[62:65], v[74:77], v[150:153], v[62:65]
	v_mfma_f32_16x16x32_bf16 v[58:61], v[86:89], v[150:153], v[58:61]
	v_mfma_f32_16x16x32_bf16 v[46:49], v[74:77], v[158:161], v[46:49]
	v_mfma_f32_16x16x32_bf16 v[42:45], v[86:89], v[158:161], v[42:45]
	v_mfma_f32_16x16x32_bf16 v[30:33], v[74:77], v[166:169], v[30:33]
	v_mfma_f32_16x16x32_bf16 v[26:29], v[86:89], v[166:169], v[26:29]
	v_mfma_f32_16x16x32_bf16 v[14:17], v[74:77], v[184:187], v[14:17]
	v_mfma_f32_16x16x32_bf16 v[10:13], v[86:89], v[184:187], v[10:13]
	s_setprio 0
	s_barrier
	s_add_u32 s22, s36, 0x100080
	s_addc_u32 s23, s37, 0
	s_add_i32 s24, s24, s52
	v_lshl_add_u64 v[70:71], s[22:23], 0, v[0:1]
	s_mov_b32 m0, s24
	s_nop 0
	global_load_lds_dwordx4 v[70:71], off
	v_lshl_add_u64 v[70:71], s[22:23], 0, v[174:175]
	s_add_i32 m0, s24, 0x2000
	s_nop 0
	global_load_lds_dwordx4 v[70:71], off
	s_waitcnt vmcnt(6)
	s_barrier
	s_setprio 1
	v_mfma_f32_16x16x32_bf16 v[54:57], v[194:197], v[146:149], v[54:57]
	v_mfma_f32_16x16x32_bf16 v[50:53], v[202:205], v[146:149], v[50:53]
	v_mfma_f32_16x16x32_bf16 v[38:41], v[194:197], v[154:157], v[38:41]
	v_mfma_f32_16x16x32_bf16 v[34:37], v[202:205], v[154:157], v[34:37]
	v_mfma_f32_16x16x32_bf16 v[22:25], v[194:197], v[162:165], v[22:25]
	v_mfma_f32_16x16x32_bf16 v[18:21], v[202:205], v[162:165], v[18:21]
	v_mfma_f32_16x16x32_bf16 v[6:9], v[194:197], v[170:173], v[6:9]
	v_mfma_f32_16x16x32_bf16 v[2:5], v[202:205], v[170:173], v[2:5]
	v_mfma_f32_16x16x32_bf16 v[54:57], v[198:201], v[150:153], v[54:57]
	v_mfma_f32_16x16x32_bf16 v[50:53], v[212:215], v[150:153], v[50:53]
	v_mfma_f32_16x16x32_bf16 v[38:41], v[198:201], v[158:161], v[38:41]
	v_mfma_f32_16x16x32_bf16 v[34:37], v[212:215], v[158:161], v[34:37]
	v_mfma_f32_16x16x32_bf16 v[22:25], v[198:201], v[166:169], v[22:25]
	v_mfma_f32_16x16x32_bf16 v[18:21], v[212:215], v[166:169], v[18:21]
	v_mfma_f32_16x16x32_bf16 v[6:9], v[198:201], v[184:187], v[6:9]
	v_mfma_f32_16x16x32_bf16 v[2:5], v[212:215], v[184:187], v[2:5]
	s_setprio 0
	s_add_i32 s64, s64, 2
	s_add_u32 s62, s62, 0x100
	s_addc_u32 s63, s63, 0
	s_cmp_gt_u32 s64, 61
	s_mov_b64 s[22:23], s[26:27]
	s_barrier
	s_cbranch_scc0 .LBB0_359
	v_lshl_add_u32 v198, s44, 8, v208
	v_lshl_or_b32 v194, s45, 8, v210
	v_ashrrev_i32_e32 v199, 31, v198
	v_ashrrev_i32_e32 v195, 31, v194
	v_lshlrev_b64 v[204:205], 13, v[198:199]
	v_or_b32_e32 v202, 16, v198
	v_lshlrev_b64 v[196:197], 2, v[194:195]
	v_lshl_add_u64 v[146:147], s[0:1], 0, v[204:205]
	v_ashrrev_i32_e32 v203, 31, v202
	v_lshl_add_u64 v[70:71], s[4:5], 0, v[196:197]
	v_lshl_add_u64 v[146:147], v[146:147], 0, v[196:197]
	v_lshlrev_b64 v[200:201], 13, v[202:203]
	global_load_dwordx4 v[86:89], v[70:71], off
	global_load_dwordx4 v[82:85], v[70:71], off offset:64
	global_load_dwordx4 v[74:77], v[70:71], off offset:512
	s_nop 0
	global_load_dwordx4 v[70:73], v[70:71], off offset:576
	s_nop 0
	global_load_dwordx4 v[184:187], v[146:147], off
	global_load_dwordx4 v[170:173], v[146:147], off offset:64
	global_load_dwordx4 v[166:169], v[146:147], off offset:512
	global_load_dwordx4 v[162:165], v[146:147], off offset:576
	v_lshl_add_u64 v[146:147], s[0:1], 0, v[200:201]
	v_lshl_add_u64 v[146:147], v[146:147], 0, v[196:197]
	global_load_dwordx4 v[158:161], v[146:147], off
	global_load_dwordx4 v[154:157], v[146:147], off offset:64
	global_load_dwordx4 v[150:153], v[146:147], off offset:512
	s_nop 0
	global_load_dwordx4 v[146:149], v[146:147], off offset:576
	v_cndmask_b32_e64 v206, 0, 1, s[10:11]
	v_lshlrev_b64 v[212:213], 11, v[198:199]
	v_lshl_add_u64 v[204:205], s[48:49], 0, v[204:205]
	v_cmp_ne_u32_e64 s[44:45], 1, v206
	s_andn2_b64 vcc, exec, s[10:11]
	v_lshl_add_u64 v[206:207], v[204:205], 0, v[196:197]
	v_lshl_add_u64 v[204:205], v[212:213], 1, s[50:51]
	s_waitcnt vmcnt(0)
	v_pk_add_f32 v[144:145], v[144:145], v[186:187]
	v_pk_add_f32 v[142:143], v[142:143], v[184:185]
	global_store_dwordx4 v[206:207], v[142:145], off
	s_cbranch_vccnz .LBB0_362
	v_pk_mul_f32 v[184:185], v[88:89], v[144:145]
	v_pk_mul_f32 v[186:187], v[86:87], v[142:143]
	s_nop 0
	v_cvt_pk_bf16_f32 v186, v186, v187
	v_cvt_pk_bf16_f32 v187, v184, v185
	v_lshl_add_u64 v[184:185], v[194:195], 1, v[204:205]
	global_store_dwordx2 v[184:185], v[186:187], off
